# LoRA-up GEMM: skip the K-tiles of the block-diagonal padded weight that are all zero (pn<8: 1 of 3 loop iterations, pn>=8: 2 of 3)
# speedup vs baseline: 1.0198x; 1.0115x over previous
; template <class Epi>
; __device__ __forceinline__ void gemm_phase(LAS unsigned char* lds, const Gemm g, const StaticOrder& S, const Epi& E) {
;     ...
;         const bool has_next = S.next(ui + 1, nxt);
;         const char* nA = has_next ? (const char*)g.A + (size_t)nxt.pm * tstepA : cA; const char* nB = has_next ? (const char*)g.Bt + (size_t)nxt.pn * tstep : cB;
; #pragma unroll 1
;         for (int t = 0; t < nt; t += 2) {
;             if constexpr (Epi::GATED) { if (t == 8 || t == 16) E.rescale(acc, cur, t == 8 ? 0 : 1, wr, wc, fr, fq); }
;             const bool last = (t == nt - 2);
;             const char* a1 = PG8_AP(cA, t + 1);
;             const char* a2 = last ? nA : PG8_AP(cA, t + 2); const char* b2 = last ? nB : cB + (size_t)(t + 2) * kstep;
;             const char* a3 = last ? nA + kstep : PG8_AP(cA, t + 3); const char* b3 = b2 + kstep;
;     ...
;         for (int a = 0; a < 2; ++a)
; #pragma unroll
;             for (int b = 0; b < 2; ++b)
; #pragma unroll
;                 for (int m = 0; m < 4; ++m)
; #pragma unroll
;                     for (int n = 0; n < 2; ++n) acc[a][b][m][n] = (f32x4){0.f, 0.f, 0.f, 0.f};
.LBB0_489:
	s_nop 0
	v_cndmask_b32_e64 v2, 0, 1, s[40:41]
	v_cmp_ne_u32_e64 s[38:39], 1, v2
	s_andn2_b64 vcc, exec, s[40:41]
	s_mov_b64 s[54:55], s[42:43]
	s_cbranch_vccnz .LBB0_491
	s_mul_i32 s13, s63, 0x30000
	s_mul_hi_i32 s12, s63, 0x30000
	s_add_u32 s54, s2, s13
	s_addc_u32 s55, s4, s12
	s_cmp_gt_i32 s52, 7
	s_cselect_b32 s12, 0x100, 0
	s_add_u32 s54, s54, s12
	s_addc_u32 s55, s55, 0
.LBB0_491:
	s_and_b64 vcc, exec, s[38:39]
	s_mov_b64 s[56:57], s[96:97]
	s_cbranch_vccnz .LBB0_493
	s_mul_i32 s13, s52, 0x30000
	s_mul_hi_i32 s12, s52, 0x30000
	s_add_u32 s56, s5, s13
	s_addc_u32 s57, s9, s12
	s_cmp_gt_i32 s52, 7
	s_cselect_b32 s12, 0x100, 0
	s_add_u32 s56, s56, s12
	s_addc_u32 s57, s57, 0
.LBB0_493:
	s_movk_i32 s100, 0x200
	s_cmp_lt_i32 s80, 8
	s_cbranch_scc1 .Lp3_mode_done
	s_movk_i32 s100, 0x100
	s_cmp_gt_i32 s47, 1
	s_cbranch_scc1 .Lp3_mode_done
	s_mov_b32 s100, 0
.Lp3_mode_done:
	s_sub_u32 s42, s42, s100
	s_subb_u32 s43, s43, 0
	s_sub_u32 s96, s96, s100
	s_subb_u32 s97, s97, 0
	s_add_u32 s81, s54, 0x80
	s_addc_u32 s85, s55, 0
	s_add_u32 s40, s42, 0x18080
	s_addc_u32 s41, s43, 0
	s_add_u32 s92, s96, 0x100
	v_mov_b32_e32 v2, 0
	v_lshl_add_u64 v[142:143], s[40:41], 0, v[138:139]
	v_lshl_add_u64 v[144:145], s[40:41], 0, v[140:141]
	s_addc_u32 s93, s97, 0
	s_lshr_b32 s94, s100, 7
	s_add_i32 s94, s94, -2
	s_mov_b32 s40, s100
	s_mov_b32 s41, 0
	v_mov_b32_e32 v3, v2
	v_mov_b32_e32 v4, v2
	v_mov_b32_e32 v5, v2
	v_mov_b32_e32 v6, v2
	v_mov_b32_e32 v7, v2
	v_mov_b32_e32 v8, v2
	v_mov_b32_e32 v9, v2
	v_mov_b32_e32 v18, v2
	v_mov_b32_e32 v19, v2
	v_mov_b32_e32 v20, v2
	v_mov_b32_e32 v21, v2
	v_mov_b32_e32 v22, v2
	v_mov_b32_e32 v23, v2
	v_mov_b32_e32 v24, v2
	v_mov_b32_e32 v25, v2
	v_mov_b32_e32 v34, v2
	v_mov_b32_e32 v35, v2
	v_mov_b32_e32 v36, v2
	v_mov_b32_e32 v37, v2
	v_mov_b32_e32 v38, v2
	v_mov_b32_e32 v39, v2
	v_mov_b32_e32 v40, v2
	v_mov_b32_e32 v41, v2
	v_mov_b32_e32 v50, v2
	v_mov_b32_e32 v51, v2
	v_mov_b32_e32 v52, v2
	v_mov_b32_e32 v53, v2
	v_mov_b32_e32 v54, v2
	v_mov_b32_e32 v55, v2
	v_mov_b32_e32 v56, v2
	v_mov_b32_e32 v57, v2
	v_mov_b32_e32 v10, v2
	v_mov_b32_e32 v11, v2
	v_mov_b32_e32 v12, v2
	v_mov_b32_e32 v13, v2
	v_mov_b32_e32 v14, v2
	v_mov_b32_e32 v15, v2
	v_mov_b32_e32 v16, v2
	v_mov_b32_e32 v17, v2
	v_mov_b32_e32 v26, v2
	v_mov_b32_e32 v27, v2
	v_mov_b32_e32 v28, v2
	v_mov_b32_e32 v29, v2
	v_mov_b32_e32 v30, v2
	v_mov_b32_e32 v31, v2
	v_mov_b32_e32 v32, v2
	v_mov_b32_e32 v33, v2
	v_mov_b32_e32 v42, v2
	v_mov_b32_e32 v43, v2
	v_mov_b32_e32 v44, v2
	v_mov_b32_e32 v45, v2
	v_mov_b32_e32 v46, v2
	v_mov_b32_e32 v47, v2
	v_mov_b32_e32 v48, v2
	v_mov_b32_e32 v49, v2
	v_mov_b32_e32 v58, v2
	v_mov_b32_e32 v59, v2
	v_mov_b32_e32 v60, v2
	v_mov_b32_e32 v61, v2
	v_mov_b32_e32 v62, v2
	v_mov_b32_e32 v63, v2
	v_mov_b32_e32 v64, v2
	v_mov_b32_e32 v65, v2
	v_mov_b32_e32 v66, v2
	v_mov_b32_e32 v67, v2
	v_mov_b32_e32 v68, v2
	v_mov_b32_e32 v69, v2
	v_mov_b32_e32 v70, v2
	v_mov_b32_e32 v71, v2
	v_mov_b32_e32 v72, v2
	v_mov_b32_e32 v73, v2
	v_mov_b32_e32 v82, v2
	v_mov_b32_e32 v83, v2
	v_mov_b32_e32 v84, v2
	v_mov_b32_e32 v85, v2
	v_mov_b32_e32 v86, v2
	v_mov_b32_e32 v87, v2
	v_mov_b32_e32 v88, v2
	v_mov_b32_e32 v89, v2
	v_mov_b32_e32 v98, v2
	v_mov_b32_e32 v99, v2
	v_mov_b32_e32 v100, v2
	v_mov_b32_e32 v101, v2
	v_mov_b32_e32 v102, v2
	v_mov_b32_e32 v103, v2
	v_mov_b32_e32 v104, v2
	v_mov_b32_e32 v105, v2
	v_mov_b32_e32 v114, v2
	v_mov_b32_e32 v115, v2
	v_mov_b32_e32 v116, v2
	v_mov_b32_e32 v117, v2
	v_mov_b32_e32 v118, v2
	v_mov_b32_e32 v119, v2
	v_mov_b32_e32 v120, v2
	v_mov_b32_e32 v121, v2
	v_mov_b32_e32 v74, v2
	v_mov_b32_e32 v75, v2
	v_mov_b32_e32 v76, v2
	v_mov_b32_e32 v77, v2
	v_mov_b32_e32 v78, v2
	v_mov_b32_e32 v79, v2
	v_mov_b32_e32 v80, v2
	v_mov_b32_e32 v81, v2
	v_mov_b32_e32 v90, v2
	v_mov_b32_e32 v91, v2
	v_mov_b32_e32 v92, v2
	v_mov_b32_e32 v93, v2
	v_mov_b32_e32 v94, v2
	v_mov_b32_e32 v95, v2
	v_mov_b32_e32 v96, v2
	v_mov_b32_e32 v97, v2
	v_mov_b32_e32 v106, v2
	v_mov_b32_e32 v107, v2
	v_mov_b32_e32 v108, v2
	v_mov_b32_e32 v109, v2
	v_mov_b32_e32 v110, v2
	v_mov_b32_e32 v111, v2
	v_mov_b32_e32 v112, v2
	v_mov_b32_e32 v113, v2
	v_mov_b32_e32 v122, v2
	v_mov_b32_e32 v123, v2
	v_mov_b32_e32 v124, v2
	v_mov_b32_e32 v125, v2
	v_mov_b32_e32 v126, v2
	v_mov_b32_e32 v127, v2
	v_mov_b32_e32 v128, v2
	v_mov_b32_e32 v129, v2
